# grid barrier after in_proj / gate_up: the first workgroup of an XCD to arrive issues an early L2 writeback (the leader's final writeback has less to flush)
# baseline (speedup 1.0000x reference)
.LBB0_40:
	s_or_b64 exec, exec, s[2:3]
	v_cvt_f32_u32_e32 v5, v2
	s_waitcnt vmcnt(0)
	v_readfirstlane_b32 s2, v4
	v_sub_u32_e32 v4, 0, v2
	v_rcp_iflag_f32_e32 v5, v5
	v_add_u32_e32 v6, s2, v1
	v_mul_f32_e32 v5, 0x4f7ffffe, v5
	v_cvt_u32_f32_e32 v5, v5
	v_mul_lo_u32 v1, v4, v5
	v_mul_hi_u32 v1, v5, v1
	v_add_u32_e32 v1, v5, v1
	v_mul_hi_u32 v1, v6, v1
	v_mul_lo_u32 v4, v1, v2
	v_sub_u32_e32 v4, v6, v4
	v_add_u32_e32 v5, 1, v1
	v_cmp_ge_u32_e32 vcc, v4, v2
	s_nop 1
	v_cndmask_b32_e32 v1, v1, v5, vcc
	v_sub_u32_e32 v5, v4, v2
	v_cndmask_b32_e32 v4, v4, v5, vcc
	v_add_u32_e32 v5, 1, v1
	v_cmp_ge_u32_e32 vcc, v4, v2
	v_add_u32_e32 v4, 1, v6
	s_nop 0
	v_cndmask_b32_e32 v1, v1, v5, vcc
	v_mul_lo_u32 v5, v2, v1
	v_add_u32_e32 v2, v5, v2
	v_cmp_ne_u32_e32 vcc, v4, v2
	s_and_saveexec_b64 s[2:3], vcc
	s_xor_b64 s[2:3], exec, s[2:3]
	s_cbranch_execz .LBB0_54
	s_cmp_eq_u32 s63, 2
	s_cselect_b32 s4, 1, 0
	s_cmp_eq_u32 s63, 7
	s_cselect_b32 s4, 1, s4
	s_cmp_eq_u32 s63, 9
	s_cselect_b32 s4, 1, s4
	s_cmp_eq_u32 s63, 14
	s_cselect_b32 s4, 1, s4
	s_cmp_eq_u32 s4, 0
	s_cbranch_scc1 .Lxb_noearly
	v_cmp_eq_u32_e32 vcc, v6, v5
	s_cbranch_vccz .Lxb_noearly
	buffer_wbl2 sc1
.Lxb_noearly:
	v_readlane_b32 s4, v254, 7
	v_readlane_b32 s5, v254, 8
	s_waitcnt lgkmcnt(0)
	s_nop 3
	global_load_dword v0, v3, s[4:5] sc1
	s_waitcnt vmcnt(0)
	v_cmp_eq_u32_e32 vcc, v0, v1
	s_and_saveexec_b64 s[4:5], vcc
	s_cbranch_execz .LBB0_53
	s_mov_b32 s8, 1
	s_mov_b64 s[6:7], 0
	s_branch .LBB0_44
